# v63 + rg1_wait (pass-1 conv wait vmcnt(2): does not drain the previous chunk's aggregate stores) + census_par (first-barrier census: 16 counter loads issued together)
# speedup vs baseline: 1.0352x; 1.0045x over previous
; __device__ __forceinline__ unsigned xb_ld(unsigned* p)              { return __hip_atomic_load(p, __ATOMIC_RELAXED, __HIP_MEMORY_SCOPE_AGENT); }
; __device__ __forceinline__ void xcd_barrier_complete(unsigned* bar, unsigned x, unsigned& nloc, unsigned& nx) {
;     const unsigned G = gridDim.x * gridDim.y * gridDim.z;
;     unsigned sum, cnt, mine, sp = 0u;
;     for (;;) {
;         sum = 0u; cnt = 0u; mine = 0u;
; #pragma unroll
;         for (unsigned j = 0; j < 16; ++j) { const unsigned c = xb_ld(&bar[XB_XCNT(j)]); sum += c; cnt += (c > 0u) ? 1u : 0u; mine = (j == x) ? c : mine; }
;         if (sum == G) break;
;         __builtin_amdgcn_s_sleep(1);
;         if ((++sp & 255u) == 0u) { if (xb_ld(&bar[XB_TMO])) break; if (sp > XB_SPIN_CAP) { atomicAdd(&bar[XB_TMO], 1u); break; } }
;     }
.LBB0_15:
	v_readlane_b32 s12, v252, 10
	v_readlane_b32 s13, v252, 11
	global_load_dword v0, v33, s[76:77] sc1
	s_mov_b64 s[14:15], -1
	s_nop 4
	global_load_dword v1, v33, s[12:13] sc1
	v_readlane_b32 s12, v252, 12
	v_readlane_b32 s13, v252, 13
	s_nop 4
	global_load_dword v2, v33, s[12:13] sc1
	v_readlane_b32 s12, v252, 14
	v_readlane_b32 s13, v252, 15
	s_nop 4
	global_load_dword v3, v33, s[12:13] sc1
	v_readlane_b32 s12, v252, 16
	v_readlane_b32 s13, v252, 17
	s_nop 4
	global_load_dword v4, v33, s[12:13] sc1
	v_readlane_b32 s12, v252, 18
	v_readlane_b32 s13, v252, 19
	s_nop 4
	global_load_dword v5, v33, s[12:13] sc1
	v_readlane_b32 s12, v252, 20
	v_readlane_b32 s13, v252, 21
	s_nop 4
	global_load_dword v6, v33, s[12:13] sc1
	v_readlane_b32 s12, v252, 22
	v_readlane_b32 s13, v252, 23
	s_nop 4
	global_load_dword v7, v33, s[12:13] sc1
	v_readlane_b32 s12, v252, 24
	v_readlane_b32 s13, v252, 25
	s_nop 4
	global_load_dword v8, v33, s[12:13] sc1
	v_readlane_b32 s12, v252, 26
	v_readlane_b32 s13, v252, 27
	s_nop 4
	global_load_dword v9, v33, s[12:13] sc1
	v_readlane_b32 s12, v252, 28
	v_readlane_b32 s13, v252, 29
	s_nop 4
	global_load_dword v10, v33, s[12:13] sc1
	v_readlane_b32 s12, v252, 30
	v_readlane_b32 s13, v252, 31
	s_nop 4
	global_load_dword v11, v33, s[12:13] sc1
	v_readlane_b32 s12, v252, 32
	v_readlane_b32 s13, v252, 33
	s_nop 4
	global_load_dword v12, v33, s[12:13] sc1
	v_readlane_b32 s12, v252, 34
	v_readlane_b32 s13, v252, 35
	s_nop 4
	global_load_dword v13, v33, s[12:13] sc1
	v_readlane_b32 s12, v252, 36
	v_readlane_b32 s13, v252, 37
	s_nop 4
	global_load_dword v14, v33, s[12:13] sc1
	v_readlane_b32 s12, v252, 38
	v_readlane_b32 s13, v252, 39
	s_nop 4
	global_load_dword v15, v33, s[12:13] sc1
	s_waitcnt vmcnt(0)
	v_add_u32_e32 v16, v1, v0
	v_add_u32_e32 v16, v16, v2
	v_add_u32_e32 v16, v16, v3
	v_add_u32_e32 v16, v16, v4
	v_add_u32_e32 v16, v16, v5
	v_add_u32_e32 v16, v16, v6
	v_add_u32_e32 v16, v16, v7
	v_add_u32_e32 v16, v16, v8
	v_add_u32_e32 v16, v16, v9
	v_add_u32_e32 v16, v16, v10
	v_add_u32_e32 v16, v16, v11
	v_add_u32_e32 v16, v16, v12
	v_add_u32_e32 v16, v16, v13
	v_add_u32_e32 v16, v16, v14
	v_add_u32_e32 v16, v16, v15
	s_mov_b64 s[12:13], -1
	v_cmp_eq_u32_e32 vcc, s0, v16
	s_cbranch_vccnz .LBB0_14
	s_and_b32 s8, s1, 0xff
	s_cmp_eq_u32 s8, 0
	s_mov_b64 s[16:17], -1
	s_sleep 1
	s_cbranch_scc1 .LBB0_19
	s_and_b64 vcc, exec, s[16:17]
	s_cbranch_vccz .LBB0_14

; template <int PASS>
; __device__ __forceinline__ void rglru_phase(const Ctx& F, int l, const bf16_t* XRb, bf16_t* GRb, bool latent_only = false) {
;     ...
;         const int ch = blk * 128 + cw + l15;
;         float nba[2], nbx[2], cl2[2];
; #pragma unroll
;         for (int d = 0; d < 2; ++d) { nba[d] = -1.4426950408889634f * P.in[14][(l * 2 + d) * 1024 + ch]; nbx[d] = -1.4426950408889634f * P.in[16][(l * 2 + d) * 1024 + ch];
;             cl2[d] = -8.0f * 1.4426950408889634f * log1pf(__expf(-P.in[17][(l * 2 + d) * 1024 + ch])); }
.LBB0_557:
	s_or_b64 exec, exec, s[12:13]
	s_cmp_lt_i32 s33, s26
	s_cbranch_scc0 .LBB0_526
	s_waitcnt vmcnt(4)
	v_mul_f32_e32 v32, 0xbfb8aa3b, v91
	v_exp_f32_e32 v32, v32
	v_mul_f32_e32 v84, 0xbfb8aa3b, v88
	s_waitcnt vmcnt(2)
	v_mul_f32_e32 v88, 0xbfb8aa3b, v90
	s_mov_b32 s8, 0x3f2aaaab
	v_add_f32_e32 v85, 1.0, v32
	v_add_f32_e32 v34, -1.0, v85
	v_sub_f32_e32 v35, v34, v85
	v_sub_f32_e32 v34, v32, v34
	v_add_f32_e32 v35, 1.0, v35
	v_add_f32_e32 v90, v34, v35
	v_frexp_mant_f32_e32 v91, v85
	v_cvt_f64_f32_e32 v[34:35], v85
	v_frexp_exp_i32_f64_e32 v34, v[34:35]
	v_cmp_gt_f32_e32 vcc, s8, v91
	s_mov_b32 s12, 0x3f317218
	s_mov_b32 s13, 0x7f800000
	v_subbrev_co_u32_e32 v34, vcc, 0, v34, vcc
	v_sub_u32_e32 v35, 0, v34
	v_ldexp_f32 v85, v85, v35
	v_ldexp_f32 v35, v90, v35
	v_add_f32_e32 v90, -1.0, v85
	v_add_f32_e32 v109, 1.0, v85
	v_add_f32_e32 v91, 1.0, v90
	v_add_f32_e32 v110, -1.0, v109
	v_sub_f32_e32 v91, v85, v91
	v_sub_f32_e32 v85, v85, v110
	v_add_f32_e32 v91, v35, v91
	v_add_f32_e32 v35, v35, v85
	v_add_f32_e32 v85, v109, v35
	v_rcp_f32_e32 v110, v85
	v_add_f32_e32 v108, v90, v91
	v_sub_f32_e32 v90, v108, v90
	v_sub_f32_e32 v90, v91, v90
	v_sub_f32_e32 v91, v85, v109
	v_sub_f32_e32 v35, v35, v91
	v_mul_f32_e32 v91, v108, v110
	v_mul_f32_e32 v109, v85, v91
	v_fma_f32 v111, v91, v85, -v109
	v_fmac_f32_e32 v111, v91, v35
	v_add_f32_e32 v112, v109, v111
	v_sub_f32_e32 v113, v108, v112
	v_sub_f32_e32 v108, v108, v113
	v_sub_f32_e32 v109, v112, v109
	v_sub_f32_e32 v108, v108, v112
	v_add_f32_e32 v90, v90, v108
	v_sub_f32_e32 v108, v109, v111
	v_add_f32_e32 v90, v108, v90
	v_add_f32_e32 v108, v113, v90
	v_mul_f32_e32 v109, v110, v108
	v_mul_f32_e32 v111, v85, v109
	v_fma_f32 v85, v109, v85, -v111
	v_fmac_f32_e32 v85, v109, v35
	v_sub_f32_e32 v35, v113, v108
	v_add_f32_e32 v35, v90, v35
	v_add_f32_e32 v90, v111, v85
	v_sub_f32_e32 v112, v108, v90
	v_sub_f32_e32 v108, v108, v112
	v_sub_f32_e32 v111, v90, v111
	v_sub_f32_e32 v90, v108, v90
	v_add_f32_e32 v35, v35, v90
	v_sub_f32_e32 v85, v111, v85
	v_cvt_f32_i32_e32 v34, v34
	v_add_f32_e32 v35, v85, v35
	v_add_f32_e32 v85, v91, v109
	v_add_f32_e32 v35, v112, v35
	v_sub_f32_e32 v90, v85, v91
	v_mul_f32_e32 v35, v110, v35
	v_sub_f32_e32 v90, v109, v90
	v_add_f32_e32 v35, v90, v35
	v_mul_f32_e32 v109, 0x3f317218, v34
	v_add_f32_e32 v90, v85, v35
	v_fma_f32 v110, v34, s12, -v109
	v_mul_f32_e32 v91, v90, v90
	v_fmac_f32_e32 v110, 0xb102e308, v34
	v_sub_f32_e32 v34, v90, v85
	v_fmamk_f32 v108, v91, 0x3e9b6dac, v218
	v_sub_f32_e32 v34, v35, v34
	v_add_f32_e32 v35, v109, v110
	v_fmaak_f32 v108, v91, v108, 0x3f2aaada
	v_sub_f32_e32 v85, v35, v109
	v_ldexp_f32 v109, v90, 1
	v_mul_f32_e32 v90, v90, v91
	v_mul_f32_e32 v90, v90, v108
	v_add_f32_e32 v91, v109, v90
	v_sub_f32_e32 v108, v91, v109
	v_ldexp_f32 v34, v34, 1
	v_sub_f32_e32 v90, v90, v108
	v_add_f32_e32 v34, v34, v90
	v_add_f32_e32 v90, v91, v34
	v_sub_f32_e32 v91, v90, v91
	v_sub_f32_e32 v34, v34, v91
	v_add_f32_e32 v91, v35, v90
	v_sub_f32_e32 v108, v91, v35
	v_sub_f32_e32 v109, v91, v108
	v_sub_f32_e32 v85, v110, v85
	v_sub_f32_e32 v35, v35, v109
	v_sub_f32_e32 v90, v90, v108
	v_add_f32_e32 v35, v90, v35
	v_add_f32_e32 v90, v85, v34
	v_sub_f32_e32 v108, v90, v85
	v_sub_f32_e32 v109, v90, v108
	v_sub_f32_e32 v85, v85, v109
	v_sub_f32_e32 v34, v34, v108
	v_add_f32_e32 v35, v90, v35
	v_add_f32_e32 v34, v34, v85
	v_add_f32_e32 v85, v91, v35
	v_sub_f32_e32 v90, v85, v91
	v_sub_f32_e32 v35, v35, v90
	v_add_f32_e32 v34, v34, v35
	v_add_f32_e32 v34, v85, v34
	v_cmp_neq_f32_e32 vcc, s13, v32
	s_mov_b32 s19, 0x33800000
	v_mul_f32_e32 v108, 0xbfb8aa3b, v86
	v_cndmask_b32_e32 v34, v216, v34, vcc
	v_cmp_ngt_f32_e32 vcc, -1.0, v32
	s_waitcnt vmcnt(1)
	v_mul_f32_e32 v112, 0xbfb8aa3b, v87
	v_mov_b32_e32 v113, v112
	v_cndmask_b32_e32 v34, v219, v34, vcc
	v_cmp_neq_f32_e32 vcc, -1.0, v32
	v_mov_b32_e32 v114, v112
	v_mov_b32_e32 v115, v112
	v_cndmask_b32_e32 v34, v247, v34, vcc
	v_cmp_lt_f32_e64 vcc, |v32|, s19
	s_nop 1
	v_cndmask_b32_e32 v32, v34, v32, vcc
	s_waitcnt vmcnt(0)
; template <int PASS>
; __device__ __forceinline__ void rglru_phase(const Ctx& F, int l, const bf16_t* XRb, bf16_t* GRb, bool latent_only = false) {
;     ...
;         float nba[2], nbx[2], cl2[2];
; #pragma unroll
;         for (int d = 0; d < 2; ++d) { nba[d] = -1.4426950408889634f * P.in[14][(l * 2 + d) * 1024 + ch]; nbx[d] = -1.4426950408889634f * P.in[16][(l * 2 + d) * 1024 + ch];
;             cl2[d] = -8.0f * 1.4426950408889634f * log1pf(__expf(-P.in[17][(l * 2 + d) * 1024 + ch])); }
;     ...
;             if (PASS == 1) { if (lane < 16) { AGG[((size_t)(b * 2 + 0) * NCH + c) * 1024 + ch] = (f32x2){aggA[0], aggB[0]}; AGG[((size_t)(b * 2 + 1) * NCH + c) * 1024 + ch] = (f32x2){aggA[1], aggB[1]}; } }
	v_mul_f32_e32 v34, 0xbfb8aa3b, v89
	v_exp_f32_e32 v85, v34
	v_mul_f32_e32 v180, 0xc138aa3b, v32
	v_add_f32_e32 v32, 1.0, v85
	v_add_f32_e32 v34, -1.0, v32
	v_sub_f32_e32 v35, v34, v32
	v_add_f32_e32 v35, 1.0, v35
	v_sub_f32_e32 v34, v85, v34
	v_add_f32_e32 v86, v34, v35
	v_frexp_mant_f32_e32 v87, v32
	v_cvt_f64_f32_e32 v[34:35], v32
	v_frexp_exp_i32_f64_e32 v34, v[34:35]
	v_cmp_gt_f32_e32 vcc, s8, v87
	s_nop 1
	v_subbrev_co_u32_e32 v34, vcc, 0, v34, vcc
	v_sub_u32_e32 v35, 0, v34
	v_ldexp_f32 v32, v32, v35
	v_ldexp_f32 v35, v86, v35
	v_add_f32_e32 v86, -1.0, v32
	v_add_f32_e32 v90, 1.0, v32
	v_add_f32_e32 v87, 1.0, v86
	v_add_f32_e32 v91, -1.0, v90
	v_sub_f32_e32 v87, v32, v87
	v_sub_f32_e32 v32, v32, v91
	v_add_f32_e32 v32, v35, v32
	v_add_f32_e32 v87, v35, v87
	v_add_f32_e32 v35, v90, v32
	v_rcp_f32_e32 v91, v35
	v_add_f32_e32 v89, v86, v87
	v_sub_f32_e32 v86, v89, v86
	v_sub_f32_e32 v86, v87, v86
	v_sub_f32_e32 v87, v35, v90
	v_sub_f32_e32 v32, v32, v87
	v_mul_f32_e32 v87, v89, v91
	v_mul_f32_e32 v90, v35, v87
	v_fma_f32 v109, v87, v35, -v90
	v_fmac_f32_e32 v109, v87, v32
	v_add_f32_e32 v110, v90, v109
	v_sub_f32_e32 v111, v89, v110
	v_sub_f32_e32 v89, v89, v111
	v_sub_f32_e32 v90, v110, v90
	v_sub_f32_e32 v89, v89, v110
	v_add_f32_e32 v86, v86, v89
	v_sub_f32_e32 v89, v90, v109
	v_add_f32_e32 v86, v89, v86
	v_add_f32_e32 v89, v111, v86
	v_mul_f32_e32 v90, v91, v89
	v_mul_f32_e32 v109, v35, v90
	v_fma_f32 v35, v90, v35, -v109
	v_fmac_f32_e32 v35, v90, v32
	v_sub_f32_e32 v32, v111, v89
	v_add_f32_e32 v32, v86, v32
	v_add_f32_e32 v86, v109, v35
	v_sub_f32_e32 v110, v89, v86
	v_sub_f32_e32 v89, v89, v110
	v_sub_f32_e32 v109, v86, v109
	v_sub_f32_e32 v86, v89, v86
	v_add_f32_e32 v32, v32, v86
	v_sub_f32_e32 v35, v109, v35
	v_cvt_f32_i32_e32 v34, v34
	v_add_f32_e32 v32, v35, v32
	v_add_f32_e32 v35, v87, v90
	v_add_f32_e32 v32, v110, v32
	v_sub_f32_e32 v86, v35, v87
	v_mul_f32_e32 v32, v91, v32
	v_sub_f32_e32 v86, v90, v86
	v_add_f32_e32 v32, v86, v32
	v_mul_f32_e32 v90, 0x3f317218, v34
	v_add_f32_e32 v86, v35, v32
	v_fma_f32 v91, v34, s12, -v90
	v_mul_f32_e32 v87, v86, v86
	v_fmac_f32_e32 v91, 0xb102e308, v34
	v_sub_f32_e32 v34, v86, v35
	v_fmamk_f32 v89, v87, 0x3e9b6dac, v218
	v_sub_f32_e32 v32, v32, v34
	v_add_f32_e32 v34, v90, v91
	v_fmaak_f32 v89, v87, v89, 0x3f2aaada
	v_sub_f32_e32 v35, v34, v90
	v_ldexp_f32 v90, v86, 1
	v_mul_f32_e32 v86, v86, v87
	v_mul_f32_e32 v86, v86, v89
	v_add_f32_e32 v87, v90, v86
	v_sub_f32_e32 v89, v87, v90
	v_ldexp_f32 v32, v32, 1
	v_sub_f32_e32 v86, v86, v89
	v_add_f32_e32 v32, v32, v86
	v_add_f32_e32 v86, v87, v32
	v_sub_f32_e32 v87, v86, v87
	v_sub_f32_e32 v32, v32, v87
	v_add_f32_e32 v87, v34, v86
	v_sub_f32_e32 v89, v87, v34
	v_sub_f32_e32 v90, v87, v89
	v_sub_f32_e32 v35, v91, v35
	v_sub_f32_e32 v34, v34, v90
	v_sub_f32_e32 v86, v86, v89
	v_add_f32_e32 v34, v86, v34
	v_add_f32_e32 v86, v35, v32
	v_sub_f32_e32 v89, v86, v35
	v_sub_f32_e32 v90, v86, v89
	v_sub_f32_e32 v35, v35, v90
	v_sub_f32_e32 v32, v32, v89
	v_add_f32_e32 v34, v86, v34
	v_add_f32_e32 v32, v32, v35
	v_add_f32_e32 v35, v87, v34
	v_sub_f32_e32 v86, v35, v87
	v_sub_f32_e32 v34, v34, v86
	v_add_f32_e32 v32, v32, v34
	v_add_f32_e32 v32, v35, v32
	v_cmp_neq_f32_e32 vcc, s13, v85
	s_and_b32 s12, s1, 7
	s_min_u32 s13, s12, 4
	v_cndmask_b32_e32 v32, v216, v32, vcc
	v_cmp_ngt_f32_e32 vcc, -1.0, v85
	s_lshl_b32 s8, s12, 9
	s_lshl_b32 s12, s12, 16
	v_cndmask_b32_e32 v32, v219, v32, vcc
	v_cmp_neq_f32_e32 vcc, -1.0, v85
	v_add_u32_e32 v34, s27, v132
	v_ashrrev_i32_e32 v35, 31, v34
	v_cndmask_b32_e32 v32, v247, v32, vcc
	v_cmp_lt_f32_e64 vcc, |v85|, s19
	s_lshl_b32 s19, s13, 6
	s_or_b32 s8, s8, s19
	s_lshl_b32 s13, s13, 13
	s_addk_i32 s8, 0xff40
	s_or_b32 s12, s12, s13
	s_lshl_b32 s13, s18, 1
	s_mul_i32 s18, s18, 0x110000
	s_mul_hi_i32 s13, s13, 0x88000
	s_add_u32 s12, s18, s12
	s_addc_u32 s13, s13, 0
	v_readlane_b32 s18, v254, 33
	s_add_u32 s12, s18, s12
	v_readlane_b32 s18, v254, 34
	v_cndmask_b32_e32 v32, v32, v85, vcc
	s_addc_u32 s13, s18, s13
	v_mul_f32_e32 v181, 0xc138aa3b, v32
	v_mov_b32_e32 v85, v84
	v_mov_b32_e32 v86, v84
	v_mov_b32_e32 v87, v84
	v_mov_b32_e32 v89, v88
	v_mov_b32_e32 v90, v88
	v_mov_b32_e32 v91, v88
	v_mov_b32_e32 v109, v108
	v_mov_b32_e32 v110, v108
	v_mov_b32_e32 v111, v108
	v_lshl_add_u64 v[142:143], v[34:35], 3, s[12:13]
	s_waitcnt vmcnt(0)
	s_branch .LBB0_560

; #define LAS __attribute__((address_space(3)))
; __device__ __forceinline__ unsigned cvt_pk_bf16(float lo, float hi) { unsigned r; asm volatile("v_cvt_pk_bf16_f32 %0, %1, %2" : "=v"(r) : "v"(lo), "v"(hi)); return r; }
; __device__ __forceinline__ float bflo(unsigned w) { return __uint_as_float(w << 16); }
; __device__ __forceinline__ float bfhi(unsigned w) { return __uint_as_float(w & 0xffff0000u); }
; template <int PASS>
; __device__ __forceinline__ void rglru_phase(const Ctx& F, int l, const bf16_t* XRb, bf16_t* GRb, bool latent_only = false) {
;     ...
;             __syncthreads();
;             {
;                 float y[16];
; #pragma unroll
;                 for (int e = 0; e < 4; ++e) { const f32x4 bv = *(const LAS f32x4*)(CW + 512 + cs + 4 * e); y[4 * e] = bv[0]; y[4 * e + 1] = bv[1]; y[4 * e + 2] = bv[2]; y[4 * e + 3] = bv[3]; }
; #pragma unroll
;                 for (int k = 0; k < 4; ++k)
; #pragma unroll
;                     for (int e = 0; e < 4; ++e) { const f32x4 wv = *(const LAS f32x4*)(CW + k * 128 + cs + 4 * e); const unsigned w0 = xin[k][e >> 1][2 * (e & 1)], w1 = xin[k][e >> 1][2 * (e & 1) + 1];
;                         y[4 * e] += bflo(w0) * wv[0]; y[4 * e + 1] += bfhi(w0) * wv[1]; y[4 * e + 2] += bflo(w1) * wv[2]; y[4 * e + 3] += bfhi(w1) * wv[3]; }
;                 u32x4 o0, o1; o0.x = cvt_pk_bf16(y[0], y[1]); o0.y = cvt_pk_bf16(y[2], y[3]); o0.z = cvt_pk_bf16(y[4], y[5]); o0.w = cvt_pk_bf16(y[6], y[7]);
;                 o1.x = cvt_pk_bf16(y[8], y[9]); o1.y = cvt_pk_bf16(y[10], y[11]); o1.z = cvt_pk_bf16(y[12], y[13]); o1.w = cvt_pk_bf16(y[14], y[15]);
;                 *(LAS u32x4*)(XT + tt * XT_LD + cs) = o0; *(LAS u32x4*)(XT + tt * XT_LD + cs + 8) = o1;
;             }
;             __syncthreads();
.LBB0_560:
	v_add_u32_e32 v32, v137, v136
	s_waitcnt lgkmcnt(0)
	s_barrier
	ds_read_b128 v[116:119], v32 offset:19456
	ds_read_b128 v[120:123], v32 offset:19472
	ds_read_b128 v[124:127], v32 offset:19488
	ds_read_b128 v[128:131], v32 offset:19504
	ds_read_b128 v[144:147], v32 offset:17408
	ds_read_b128 v[148:151], v32 offset:17424
	ds_read_b128 v[152:155], v32 offset:17440
	ds_read_b128 v[160:163], v32 offset:17456
	ds_read_b128 v[182:185], v32 offset:17920
	ds_read_b128 v[186:189], v32 offset:17936
	ds_read_b128 v[190:193], v32 offset:17952
	ds_read_b128 v[194:197], v32 offset:17968
	ds_read_b128 v[198:201], v32 offset:18432
	ds_read_b128 v[206:209], v32 offset:18448
	ds_read_b128 v[210:213], v32 offset:18464
	ds_read_b128 v[220:223], v32 offset:18480
	ds_read_b128 v[224:227], v32 offset:18944
	ds_read_b128 v[228:231], v32 offset:18960
	ds_read_b128 v[232:235], v32 offset:18976
	ds_read_b128 v[236:239], v32 offset:18992
	s_waitcnt vmcnt(2)
	s_add_i32 s27, s33, 1
	s_cmp_ge_u32 s27, s26
	s_cselect_b64 s[12:13], -1, 0
	s_waitcnt lgkmcnt(12)
	v_lshlrev_b32_e32 v34, 16, v72
	v_and_b32_e32 v35, 0xffff0000, v72
	v_pk_mul_f32 v[34:35], v[144:145], v[34:35]
	v_pk_add_f32 v[116:117], v[116:117], v[34:35]
	v_lshlrev_b32_e32 v164, 16, v73
	v_and_b32_e32 v165, 0xffff0000, v73
	v_pk_mul_f32 v[164:165], v[146:147], v[164:165]
	v_pk_add_f32 v[118:119], v[118:119], v[164:165]
	v_lshlrev_b32_e32 v240, 16, v74
	v_and_b32_e32 v241, 0xffff0000, v74
	v_pk_mul_f32 v[240:241], v[148:149], v[240:241]
	v_pk_add_f32 v[120:121], v[120:121], v[240:241]
	v_lshlrev_b32_e32 v34, 16, v75
	v_and_b32_e32 v35, 0xffff0000, v75
	v_pk_mul_f32 v[34:35], v[150:151], v[34:35]
	v_pk_add_f32 v[122:123], v[122:123], v[34:35]
	v_lshlrev_b32_e32 v164, 16, v68
	v_and_b32_e32 v165, 0xffff0000, v68
	v_pk_mul_f32 v[164:165], v[152:153], v[164:165]
	v_pk_add_f32 v[124:125], v[124:125], v[164:165]
	v_lshlrev_b32_e32 v240, 16, v69
	v_and_b32_e32 v241, 0xffff0000, v69
	v_pk_mul_f32 v[240:241], v[154:155], v[240:241]
	v_pk_add_f32 v[126:127], v[126:127], v[240:241]
	v_lshlrev_b32_e32 v34, 16, v70
	v_and_b32_e32 v35, 0xffff0000, v70
	v_pk_mul_f32 v[34:35], v[160:161], v[34:35]
	v_pk_add_f32 v[128:129], v[128:129], v[34:35]
	v_lshlrev_b32_e32 v164, 16, v71
	v_and_b32_e32 v165, 0xffff0000, v71
	v_pk_mul_f32 v[164:165], v[162:163], v[164:165]
	v_pk_add_f32 v[130:131], v[130:131], v[164:165]
	s_waitcnt lgkmcnt(8)
	v_lshlrev_b32_e32 v240, 16, v80
	v_and_b32_e32 v241, 0xffff0000, v80
	v_pk_mul_f32 v[240:241], v[182:183], v[240:241]
	v_pk_add_f32 v[116:117], v[116:117], v[240:241]
	v_lshlrev_b32_e32 v34, 16, v81
	v_and_b32_e32 v35, 0xffff0000, v81
	v_pk_mul_f32 v[34:35], v[184:185], v[34:35]
	v_pk_add_f32 v[118:119], v[118:119], v[34:35]
	v_lshlrev_b32_e32 v164, 16, v82
	v_and_b32_e32 v165, 0xffff0000, v82
	v_pk_mul_f32 v[164:165], v[186:187], v[164:165]
	v_pk_add_f32 v[120:121], v[120:121], v[164:165]
	v_lshlrev_b32_e32 v240, 16, v83
	v_and_b32_e32 v241, 0xffff0000, v83
	v_pk_mul_f32 v[240:241], v[188:189], v[240:241]
	v_pk_add_f32 v[122:123], v[122:123], v[240:241]
	v_lshlrev_b32_e32 v34, 16, v76
	v_and_b32_e32 v35, 0xffff0000, v76
	v_pk_mul_f32 v[34:35], v[190:191], v[34:35]
	v_pk_add_f32 v[124:125], v[124:125], v[34:35]
	v_lshlrev_b32_e32 v164, 16, v77
	v_and_b32_e32 v165, 0xffff0000, v77
	v_pk_mul_f32 v[164:165], v[192:193], v[164:165]
	v_pk_add_f32 v[126:127], v[126:127], v[164:165]
	v_lshlrev_b32_e32 v240, 16, v78
	v_and_b32_e32 v241, 0xffff0000, v78
	v_pk_mul_f32 v[240:241], v[194:195], v[240:241]
	v_pk_add_f32 v[128:129], v[128:129], v[240:241]
	v_lshlrev_b32_e32 v34, 16, v79
	v_and_b32_e32 v35, 0xffff0000, v79
	v_pk_mul_f32 v[34:35], v[196:197], v[34:35]
	v_pk_add_f32 v[130:131], v[130:131], v[34:35]
	s_waitcnt lgkmcnt(4)
	v_lshlrev_b32_e32 v164, 16, v96
	v_and_b32_e32 v165, 0xffff0000, v96
	v_pk_mul_f32 v[164:165], v[198:199], v[164:165]
	v_pk_add_f32 v[116:117], v[116:117], v[164:165]
	v_lshlrev_b32_e32 v240, 16, v97
	v_and_b32_e32 v241, 0xffff0000, v97
	v_pk_mul_f32 v[240:241], v[200:201], v[240:241]
	v_pk_add_f32 v[118:119], v[118:119], v[240:241]
	v_lshlrev_b32_e32 v34, 16, v98
	v_and_b32_e32 v35, 0xffff0000, v98
	v_pk_mul_f32 v[34:35], v[206:207], v[34:35]
	v_pk_add_f32 v[120:121], v[120:121], v[34:35]
	v_lshlrev_b32_e32 v164, 16, v99
	v_and_b32_e32 v165, 0xffff0000, v99
	v_pk_mul_f32 v[164:165], v[208:209], v[164:165]
	v_pk_add_f32 v[122:123], v[122:123], v[164:165]
	v_lshlrev_b32_e32 v240, 16, v92
	v_and_b32_e32 v241, 0xffff0000, v92
	v_pk_mul_f32 v[240:241], v[210:211], v[240:241]
	v_pk_add_f32 v[124:125], v[124:125], v[240:241]
	v_lshlrev_b32_e32 v34, 16, v93
	v_and_b32_e32 v35, 0xffff0000, v93
	v_pk_mul_f32 v[34:35], v[212:213], v[34:35]
	v_pk_add_f32 v[126:127], v[126:127], v[34:35]
	v_lshlrev_b32_e32 v164, 16, v94
	v_and_b32_e32 v165, 0xffff0000, v94
	v_pk_mul_f32 v[164:165], v[220:221], v[164:165]
	v_pk_add_f32 v[128:129], v[128:129], v[164:165]
	v_lshlrev_b32_e32 v240, 16, v95
	v_and_b32_e32 v241, 0xffff0000, v95
	v_pk_mul_f32 v[240:241], v[222:223], v[240:241]
	v_pk_add_f32 v[130:131], v[130:131], v[240:241]
	s_waitcnt lgkmcnt(0)
	v_lshlrev_b32_e32 v34, 16, v104
	v_and_b32_e32 v35, 0xffff0000, v104
	v_pk_mul_f32 v[34:35], v[224:225], v[34:35]
	v_pk_add_f32 v[116:117], v[116:117], v[34:35]
	v_lshlrev_b32_e32 v164, 16, v105
	v_and_b32_e32 v165, 0xffff0000, v105
	v_pk_mul_f32 v[164:165], v[226:227], v[164:165]
	v_pk_add_f32 v[118:119], v[118:119], v[164:165]
	v_lshlrev_b32_e32 v240, 16, v106
	v_and_b32_e32 v241, 0xffff0000, v106
	v_pk_mul_f32 v[240:241], v[228:229], v[240:241]
	v_pk_add_f32 v[120:121], v[120:121], v[240:241]
	v_lshlrev_b32_e32 v34, 16, v107
	v_and_b32_e32 v35, 0xffff0000, v107
	v_pk_mul_f32 v[34:35], v[230:231], v[34:35]
	v_pk_add_f32 v[122:123], v[122:123], v[34:35]
	v_lshlrev_b32_e32 v164, 16, v100
	v_and_b32_e32 v165, 0xffff0000, v100
	v_pk_mul_f32 v[164:165], v[232:233], v[164:165]
	v_pk_add_f32 v[124:125], v[124:125], v[164:165]
	v_lshlrev_b32_e32 v240, 16, v101
	v_and_b32_e32 v241, 0xffff0000, v101
	v_pk_mul_f32 v[240:241], v[234:235], v[240:241]
	v_pk_add_f32 v[126:127], v[126:127], v[240:241]
	v_lshlrev_b32_e32 v34, 16, v102
	v_and_b32_e32 v35, 0xffff0000, v102
	v_pk_mul_f32 v[34:35], v[236:237], v[34:35]
	v_pk_add_f32 v[128:129], v[128:129], v[34:35]
	v_lshlrev_b32_e32 v164, 16, v103
	v_and_b32_e32 v165, 0xffff0000, v103
	v_pk_mul_f32 v[164:165], v[238:239], v[164:165]
	v_pk_add_f32 v[130:131], v[130:131], v[164:165]
	v_cvt_pk_bf16_f32 v144, v116, v117
	v_cvt_pk_bf16_f32 v145, v118, v119
	v_cvt_pk_bf16_f32 v146, v120, v121
	v_cvt_pk_bf16_f32 v147, v122, v123
	v_cvt_pk_bf16_f32 v148, v124, v125
	v_cvt_pk_bf16_f32 v149, v126, v127
	v_cvt_pk_bf16_f32 v150, v128, v129
	v_cvt_pk_bf16_f32 v151, v130, v131
	ds_write_b128 v177, v[144:147]
	ds_write_b128 v177, v[148:151] offset:16
	s_and_b64 vcc, exec, s[12:13]
	s_waitcnt lgkmcnt(0)
	s_barrier
; template <int PASS>
; __device__ __forceinline__ void rglru_phase(const Ctx& F, int l, const bf16_t* XRb, bf16_t* GRb, bool latent_only = false) {
;     ...
;             if (c + 1 < c1) RG_LOADX(c + 1);
	s_cbranch_vccnz .LBB0_570
	s_add_i32 s18, s8, 0x100
	s_cmp_lt_u32 s33, 3
	s_cselect_b32 s18, s18, s8
	v_add_u32_e32 v102, s18, v158
	s_cselect_b32 s38, 0x100, s10
	v_add_u32_e32 v32, -2, v102
	v_mov_b32_e32 v76, 0
	v_mov_b32_e32 v77, v33
	v_cmp_lt_i32_e32 vcc, 1, v102
	v_cmp_gt_i32_e64 s[52:53], s38, v32
	v_mov_b32_e32 v78, v33
	v_mov_b32_e32 v79, v33
	v_mov_b64_e32 v[68:69], v[76:77]
	v_mov_b64_e32 v[72:73], v[76:77]
	s_cselect_b32 s33, s22, s23
	s_and_b64 s[52:53], vcc, s[52:53]
	v_mov_b64_e32 v[70:71], v[78:79]
	v_mov_b64_e32 v[74:75], v[78:79]
	s_and_saveexec_b64 s[18:19], s[52:53]
	s_cbranch_execz .LBB0_563
	v_add_u32_e32 v34, s33, v32
	v_ashrrev_i32_e32 v35, 31, v34
	v_lshlrev_b64 v[34:35], 11, v[34:35]
	v_lshl_add_u64 v[34:35], v[140:141], 0, v[34:35]
	global_load_dwordx4 v[68:71], v[34:35], off offset:16
	global_load_dwordx4 v[72:75], v[34:35], off
